# attention: waits moved to first consumer (7.2): V-tile LDS staging (vmcnt waits + ds_writes) and the next-tile K prefetch moved from between the QK MFMAs to just before the transposed V reads, so the
# speedup vs baseline: 1.0008x; 1.0008x over previous
.LBB0_627:
	s_add_i32 s2, s39, s46
	s_addk_i32 s2, 0xff80
	s_cmp_lt_i32 s2, 0
	s_cbranch_scc1 .Lmy_kpf_skip
	v_add_u32_e32 v34, s46, v89
	v_add_u32_e32 v0, 0xffffff80, v34
	v_lshlrev_b64 v[38:39], s19, v[0:1]
	v_add_u32_e32 v0, 0xffffff88, v34
	v_lshlrev_b64 v[114:115], s19, v[0:1]
	v_add_u32_e32 v0, 0xffffff90, v34
	v_lshlrev_b64 v[150:151], s19, v[0:1]
	v_add_u32_e32 v0, 0xffffff98, v34
	v_lshlrev_b64 v[152:153], s19, v[0:1]
	v_mad_u64_u32 v[40:41], s[2:3], v38, s20, v[98:99]
	v_mad_u32_u24 v41, v39, s20, v41
	v_and_b32_e32 v38, 64, v125
	global_load_dwordx4 v[146:149], v[40:41], off offset:3072
	v_add_u32_e32 v96, 64, v38
	v_add_u32_e32 v175, v132, v67
	v_add_u32_e32 v176, v132, v66
	v_cvt_f32_i32_e32 v157, v175
	v_cvt_f32_i32_e32 v156, v176
	v_add_u32_e32 v177, v69, v132
	v_add_u32_e32 v178, v68, v132
	v_cvt_f32_i32_e32 v159, v177
	v_cvt_f32_i32_e32 v158, v178
	v_xor_b32_e32 v0, 32, v125
	v_add_u32_e32 v168, v74, v132
	v_add_u32_e32 v179, v71, v132
	v_add_u32_e32 v180, v70, v132
	v_cvt_f32_i32_e32 v91, v168
	v_cvt_f32_i32_e32 v161, v179
	v_cvt_f32_i32_e32 v160, v180
	v_cmp_lt_i32_e32 vcc, v0, v96
	v_pk_mul_f32 v[156:157], v[102:103], v[156:157]
	v_pk_mul_f32 v[158:159], v[102:103], v[158:159]
	v_cndmask_b32_e32 v0, v125, v0, vcc
	v_cmp_gt_u32_e32 vcc, s21, v175
	v_lshlrev_b32_e32 v184, 2, v0
	v_add_u32_e32 v163, v75, v132
	v_mad_u64_u32 v[166:167], s[2:3], v114, s20, v[98:99]
	v_pk_mul_f32 v[160:161], v[102:103], v[160:161]
	v_mad_u32_u24 v167, v115, s20, v167
	v_mad_u64_u32 v[114:115], s[2:3], v150, s20, v[98:99]
	v_mad_u32_u24 v115, v151, s20, v115
	v_mad_u64_u32 v[150:151], s[2:3], v152, s20, v[98:99]
	v_mov_b32_e32 v155, v97
	v_add_u32_e32 v170, v76, v132
	v_mad_u32_u24 v151, v153, s20, v151
	global_load_dwordx4 v[186:189], v[166:167], off offset:3072
	global_load_dwordx4 v[190:193], v[114:115], off offset:3072
	global_load_dwordx4 v[194:197], v[150:151], off offset:3072
	v_mov_b32_e32 v117, v97
	v_add_u32_e32 v169, v77, v132
	v_mov_b32_e32 v113, v97
	v_add_u32_e32 v172, v78, v132
	v_mov_b32_e32 v111, v97
	v_add_u32_e32 v174, v80, v132
	v_mov_b32_e32 v109, v97
	v_add_u32_e32 v171, v79, v132
	v_mov_b32_e32 v107, v97
	v_add_u32_e32 v173, v81, v132
	v_mov_b32_e32 v105, v97
	v_add_u32_e32 v182, v73, v132
	v_add_u32_e32 v183, v72, v132
	v_cvt_f32_i32_e32 v165, v182
	v_cvt_f32_i32_e32 v164, v183
	s_waitcnt vmcnt(7)
	v_mfma_f32_32x32x16_bf16 v[34:49], v[212:215], v[50:53], 0
	s_waitcnt vmcnt(6)
	v_mfma_f32_32x32x16_bf16 v[34:49], v[216:219], v[54:57], v[34:49]
	s_waitcnt vmcnt(5)
	v_mfma_f32_32x32x16_bf16 v[34:49], v[220:223], v[58:61], v[34:49]
	s_waitcnt vmcnt(4)
	v_mfma_f32_32x32x16_bf16 v[34:49], v[224:227], v[62:65], v[34:49]
	s_nop 11
	v_mov_b32_e32 v96, v42
	v_mov_b32_e32 v116, v43
	v_mov_b32_e32 v42, v34
	v_mov_b32_e32 v43, v36
	v_pk_fma_f32 v[42:43], v[42:43], s[16:17], v[156:157] op_sel_hi:[1,0,1] neg_lo:[0,0,1] neg_hi:[0,0,1]
	v_mov_b32_e32 v36, v35
	v_cndmask_b32_e32 v0, v126, v43, vcc
	v_cmp_gt_u32_e32 vcc, s21, v176
	v_mov_b32_e32 v110, v46
	v_pk_fma_f32 v[36:37], v[36:37], s[16:17], v[158:159] op_sel_hi:[1,0,1] neg_lo:[0,0,1] neg_hi:[0,0,1]
	v_cndmask_b32_e32 v46, v126, v42, vcc
	v_cmp_gt_u32_e32 vcc, s21, v177
	v_mov_b32_e32 v108, v47
	v_mov_b32_e32 v34, v38
	v_mov_b32_e32 v35, v40
	v_mov_b32_e32 v40, v39
	v_pk_mul_f32 v[38:39], v[96:97], v[90:91]
	v_cvt_f32_i32_e32 v91, v163
	v_cndmask_b32_e32 v47, v126, v37, vcc
	v_cmp_gt_u32_e32 vcc, s21, v178
	v_mov_b32_e32 v106, v48
	v_pk_fma_f32 v[34:35], v[34:35], s[16:17], v[160:161] op_sel_hi:[1,0,1] neg_lo:[0,0,1] neg_hi:[0,0,1]
	v_cndmask_b32_e32 v48, v126, v36, vcc
	v_cmp_gt_u32_e32 vcc, s21, v179
	v_mov_b32_e32 v104, v49
	v_mov_b32_e32 v154, v44
	v_cndmask_b32_e32 v49, v126, v35, vcc
	v_cmp_gt_u32_e32 vcc, s21, v180
	v_mov_b32_e32 v112, v45
	v_mov_b32_e32 v44, v38
	v_cndmask_b32_e32 v96, v126, v34, vcc
	v_max3_f32 v34, v46, s22, v48
	v_max3_f32 v114, v34, v0, v47
	v_pk_mul_f32 v[34:35], v[154:155], v[90:91]
	v_cvt_f32_i32_e32 v91, v170
	v_mov_b32_e32 v45, v34
	v_mov_b32_e32 v34, v39
	v_pk_add_f32 v[34:35], v[44:45], v[34:35] neg_lo:[0,1] neg_hi:[0,1]
	v_pk_mul_f32 v[36:37], v[116:117], v[90:91]
	v_cvt_f32_i32_e32 v91, v169
	v_cmp_gt_u32_e32 vcc, s21, v163
	v_mov_b32_e32 v38, v36
	s_nop 0
	v_cndmask_b32_e32 v44, v126, v35, vcc
	v_cmp_gt_u32_e32 vcc, s21, v168
	s_nop 1
	v_cndmask_b32_e32 v45, v126, v34, vcc
	v_pk_mul_f32 v[34:35], v[112:113], v[90:91]
	v_cvt_f32_i32_e32 v91, v172
	v_mov_b32_e32 v39, v34
	v_mov_b32_e32 v34, v37
	v_pk_add_f32 v[34:35], v[38:39], v[34:35] neg_lo:[0,1] neg_hi:[0,1]
	v_pk_mul_f32 v[36:37], v[110:111], v[90:91]
	v_cvt_f32_i32_e32 v91, v174
	v_cmp_gt_u32_e32 vcc, s21, v169
	v_pk_mul_f32 v[38:39], v[108:109], v[90:91]
	v_cvt_f32_i32_e32 v91, v171
	v_cndmask_b32_e32 v110, v126, v35, vcc
	v_cmp_gt_u32_e32 vcc, s21, v170
	v_pk_mul_f32 v[42:43], v[106:107], v[90:91]
	v_cvt_f32_i32_e32 v91, v173
	v_cndmask_b32_e32 v108, v126, v34, vcc
	v_mov_b32_e32 v34, v36
	v_mov_b32_e32 v35, v42
	v_mov_b32_e32 v42, v37
	v_pk_add_f32 v[34:35], v[34:35], v[42:43] neg_lo:[0,1] neg_hi:[0,1]
	v_cmp_gt_u32_e32 vcc, s21, v171
	v_mov_b32_e32 v36, v38
	s_nop 0
	v_cndmask_b32_e32 v42, v126, v35, vcc
	v_cmp_gt_u32_e32 vcc, s21, v172
	s_nop 1
	v_cndmask_b32_e32 v43, v126, v34, vcc
	v_pk_mul_f32 v[34:35], v[104:105], v[90:91]
	v_cmp_gt_u32_e32 vcc, s21, v173
	v_mov_b32_e32 v37, v34
	v_mov_b32_e32 v34, v39
	v_pk_add_f32 v[34:35], v[36:37], v[34:35] neg_lo:[0,1] neg_hi:[0,1]
	s_nop 0
	v_cndmask_b32_e32 v91, v126, v35, vcc
	v_cmp_gt_u32_e32 vcc, s21, v174
	s_nop 1
	v_cndmask_b32_e32 v104, v126, v34, vcc
	v_pk_mul_f32 v[34:35], v[102:103], v[164:165]
	v_cmp_gt_u32_e32 vcc, s21, v182
	v_pk_fma_f32 v[34:35], v[40:41], s[16:17], v[34:35] op_sel_hi:[1,0,1] neg_lo:[0,0,1] neg_hi:[0,0,1]
	s_nop 0
	v_cndmask_b32_e32 v105, v126, v35, vcc
	v_cmp_gt_u32_e32 vcc, s21, v183
	s_nop 1
	v_cndmask_b32_e32 v106, v126, v34, vcc
	v_max3_f32 v34, v114, v96, v106
	v_max3_f32 v34, v34, v49, v105
	v_max3_f32 v34, v34, v45, v108
	v_max3_f32 v34, v34, v44, v110
	v_max3_f32 v34, v34, v43, v104
	v_max3_f32 v34, v34, v42, v91
	ds_bpermute_b32 v35, v184, v34
	s_waitcnt lgkmcnt(0)
	v_max3_f32 v107, v133, v34, v35
	v_sub_f32_e32 v34, v46, v107
	v_sub_f32_e32 v111, v133, v107
	v_mov_b32_e32 v133, v107
	v_exp_f32_e32 v109, v34
	s_waitcnt vmcnt(3)
	ds_write_b128 v123, v[146:149]
	s_waitcnt vmcnt(2)
	ds_write_b128 v123, v[186:189] offset:1024
	s_waitcnt vmcnt(1)
	ds_write_b128 v123, v[190:193] offset:2048
	s_waitcnt vmcnt(0)
	ds_write_b128 v123, v[194:197] offset:3072
	s_cmp_eq_u32 s56, 1
	s_cbranch_scc1 .Lmy_kpf_b
	s_add_i32 s98, s46, 32
	s_cmpk_lg_i32 s98, 0xa0
	s_cselect_b32 s98, s98, 0
	s_add_i32 s99, s39, s98
	s_addk_i32 s99, 0xff80
	s_cmp_lt_i32 s99, 0
	s_cbranch_scc1 .Lmy_kpf_b
	v_add_u32_e32 v228, s98, v131
	v_mov_b32_e32 v229, 0
	v_lshlrev_b64 v[230:231], s19, v[228:229]
	v_mad_u64_u32 v[232:233], s[100:101], v230, s20, v[100:101]
	v_mad_u32_u24 v233, v231, s20, v233
	global_load_dwordx4 v[212:215], v[232:233], off offset:1536
	global_load_dwordx4 v[216:219], v[232:233], off offset:1568
	global_load_dwordx4 v[220:223], v[232:233], off offset:1600
	global_load_dwordx4 v[224:227], v[232:233], off offset:1632
.Lmy_kpf_b:
	s_waitcnt lgkmcnt(0)
	ds_read_b64_tr_b16 v[38:39], v124
	ds_read_b64_tr_b16 v[40:41], v124 offset:1024
	ds_read_b64_tr_b16 v[36:37], v124 offset:1088
	ds_read_b64_tr_b16 v[34:35], v124 offset:64
	v_sub_f32_e32 v112, v48, v107
	s_nop 1
	v_sub_f32_e32 v113, v0, v107
	v_exp_f32_e32 v112, v112
	s_nop 0
	v_exp_f32_e32 v113, v113
	v_cmp_lt_f32_e32 vcc, s23, v0
	v_sub_f32_e32 v0, v47, v107
	v_cmp_lt_f32_e64 s[2:3], s23, v46
	v_cndmask_b32_e32 v113, 0, v113, vcc
	s_nop 0
	v_cndmask_b32_e64 v46, 0, v109, s[2:3]
	s_nop 0
	v_exp_f32_e32 v0, v0
	v_cmp_lt_f32_e32 vcc, s23, v47
	s_nop 0
	s_nop 0
	v_cndmask_b32_e32 v47, 0, v0, vcc
	v_cmp_lt_f32_e32 vcc, s23, v48
	v_sub_f32_e32 v0, v96, v107
	s_nop 0
	v_cndmask_b32_e32 v48, 0, v112, vcc
	s_nop 1
	v_sub_f32_e32 v109, v49, v107
	v_exp_f32_e32 v0, v0
	s_nop 0
	v_exp_f32_e32 v109, v109
	v_cmp_lt_f32_e32 vcc, s23, v49
	s_nop 1
	v_cndmask_b32_e32 v49, 0, v109, vcc
	v_cmp_lt_f32_e32 vcc, s23, v96
	s_nop 1
	v_cndmask_b32_e32 v96, 0, v0, vcc
	v_sub_f32_e32 v0, v106, v107
	s_nop 1
	v_sub_f32_e32 v109, v105, v107
	v_exp_f32_e32 v0, v0
	s_nop 0
	v_exp_f32_e32 v109, v109
	v_cmp_lt_f32_e32 vcc, s23, v105
	s_nop 1
	v_cndmask_b32_e32 v105, 0, v109, vcc
	v_cmp_lt_f32_e32 vcc, s23, v106
	s_nop 1
	v_cndmask_b32_e32 v106, 0, v0, vcc
	v_sub_f32_e32 v0, v45, v107
	s_nop 1
	v_sub_f32_e32 v109, v44, v107
	v_exp_f32_e32 v0, v0
	s_nop 0
	v_exp_f32_e32 v109, v109
	v_cmp_lt_f32_e32 vcc, s23, v44
	s_nop 1
	v_cndmask_b32_e32 v109, 0, v109, vcc
	v_cmp_lt_f32_e32 vcc, s23, v45
	s_nop 1
	v_cndmask_b32_e32 v112, 0, v0, vcc
	v_sub_f32_e32 v0, v108, v107
	s_nop 1
	v_sub_f32_e32 v44, v110, v107
	v_exp_f32_e32 v0, v0
	s_nop 0
	v_exp_f32_e32 v44, v44
	v_cmp_lt_f32_e32 vcc, s23, v110
	s_nop 1
	v_cndmask_b32_e32 v110, 0, v44, vcc
	v_cmp_lt_f32_e32 vcc, s23, v108
	s_nop 1
	v_cndmask_b32_e32 v108, 0, v0, vcc
	v_sub_f32_e32 v0, v43, v107
	s_nop 1
	v_sub_f32_e32 v44, v42, v107
	v_exp_f32_e32 v0, v0
	s_nop 0
	v_exp_f32_e32 v44, v44
	v_cmp_lt_f32_e32 vcc, s23, v42
	v_bfe_u32 v45, v48, 16, 1
	s_nop 0
	v_cndmask_b32_e32 v114, 0, v44, vcc
	v_cmp_lt_f32_e32 vcc, s23, v43
	v_bfe_u32 v44, v47, 16, 1
	s_nop 0
	v_cndmask_b32_e32 v115, 0, v0, vcc
	v_sub_f32_e32 v0, v104, v107
	s_nop 1
	v_sub_f32_e32 v42, v91, v107
	v_exp_f32_e32 v0, v0
	s_nop 0
	v_exp_f32_e32 v42, v42
	v_cmp_lt_f32_e32 vcc, s23, v91
	v_bfe_u32 v43, v106, 16, 1
	v_add3_u32 v43, v106, v43, s28
	v_cndmask_b32_e32 v91, 0, v42, vcc
	v_cmp_lt_f32_e32 vcc, s23, v104
	s_nop 1
	v_cndmask_b32_e32 v104, 0, v0, vcc
	v_add_f32_e32 v0, v46, v48
	v_add_f32_e32 v0, v113, v0
	v_add_f32_e32 v0, v47, v0
	v_add_f32_e32 v0, v96, v0
	v_add_f32_e32 v0, v106, v0
	v_add_f32_e32 v0, v49, v0
	v_add_f32_e32 v0, v105, v0
	v_add_f32_e32 v0, v112, v0
	v_add_f32_e32 v0, v108, v0
	v_add_f32_e32 v0, v109, v0
	v_mov_b32_e32 v42, v111
	v_add_f32_e32 v0, v110, v0
	v_exp_f32_e32 v42, v42
	v_add_f32_e32 v0, v115, v0
	v_add_f32_e32 v0, v104, v0
	v_add_f32_e32 v111, v114, v0
	v_mov_b32_e32 v0, v42
	v_bfe_u32 v42, v105, 16, 1
	v_add3_u32 v48, v48, v45, s28
	v_add3_u32 v47, v47, v44, s28
	v_add3_u32 v42, v105, v42, s28
	v_bfe_u32 v44, v46, 16, 1
	v_bfe_u32 v45, v113, 16, 1
	v_bfe_u32 v105, v96, 16, 1
	v_bfe_u32 v106, v49, 16, 1
	v_add3_u32 v49, v49, v106, s28
	v_add3_u32 v96, v96, v105, s28
	v_add3_u32 v45, v113, v45, s28
	v_add3_u32 v44, v46, v44, s28
	v_lshrrev_b32_e32 v46, 16, v44
	v_lshrrev_b32_e32 v105, 16, v45
	v_lshrrev_b32_e32 v44, 16, v96
	v_lshrrev_b32_e32 v45, 16, v49
	v_pk_mul_f32 v[32:33], v[32:33], v[0:1] op_sel_hi:[1,0]
	v_pk_mul_f32 v[30:31], v[30:31], v[0:1] op_sel_hi:[1,0]
	v_pk_mul_f32 v[28:29], v[28:29], v[0:1] op_sel_hi:[1,0]
	v_pk_mul_f32 v[26:27], v[26:27], v[0:1] op_sel_hi:[1,0]
	v_pk_mul_f32 v[24:25], v[24:25], v[0:1] op_sel_hi:[1,0]
	v_pk_mul_f32 v[22:23], v[22:23], v[0:1] op_sel_hi:[1,0]
	v_pk_mul_f32 v[20:21], v[20:21], v[0:1] op_sel_hi:[1,0]
	v_pk_mul_f32 v[18:19], v[18:19], v[0:1] op_sel_hi:[1,0]
	v_pk_mul_f32 v[16:17], v[16:17], v[0:1] op_sel_hi:[1,0]
	v_and_or_b32 v45, v42, s29, v45
	v_and_or_b32 v44, v43, s29, v44
	v_and_or_b32 v43, v47, s29, v105
	v_and_or_b32 v42, v48, s29, v46
	v_pk_mul_f32 v[14:15], v[14:15], v[0:1] op_sel_hi:[1,0]
	v_pk_mul_f32 v[12:13], v[12:13], v[0:1] op_sel_hi:[1,0]
	v_pk_mul_f32 v[10:11], v[10:11], v[0:1] op_sel_hi:[1,0]
	v_pk_mul_f32 v[8:9], v[8:9], v[0:1] op_sel_hi:[1,0]
	v_pk_mul_f32 v[6:7], v[6:7], v[0:1] op_sel_hi:[1,0]
	v_pk_mul_f32 v[4:5], v[4:5], v[0:1] op_sel_hi:[1,0]
	v_pk_mul_f32 v[2:3], v[2:3], v[0:1] op_sel_hi:[1,0]
	s_waitcnt lgkmcnt(2)
	v_mfma_f32_32x32x16_bf16 v[18:33], v[38:41], v[42:45], v[18:33]
	s_waitcnt lgkmcnt(0)
	v_mfma_f32_32x32x16_bf16 v[2:17], v[34:37], v[42:45], v[2:17]
	v_bfe_u32 v34, v91, 16, 1
	v_bfe_u32 v35, v104, 16, 1
	v_bfe_u32 v36, v110, 16, 1
	v_bfe_u32 v37, v108, 16, 1
	v_add3_u32 v38, v108, v37, s28
	v_add3_u32 v39, v110, v36, s28
	v_add3_u32 v40, v104, v35, s28
	v_add3_u32 v41, v91, v34, s28
	v_bfe_u32 v34, v112, 16, 1
	v_bfe_u32 v35, v109, 16, 1
	v_bfe_u32 v36, v115, 16, 1
	v_bfe_u32 v37, v114, 16, 1
	v_add3_u32 v42, v114, v37, s28
	v_add3_u32 v43, v115, v36, s28
	v_add3_u32 v35, v109, v35, s28
	v_add3_u32 v34, v112, v34, s28
	v_lshrrev_b32_e32 v44, 16, v34
	v_lshrrev_b32_e32 v45, 16, v35
	ds_read_b64_tr_b16 v[34:35], v124 offset:2048
	ds_read_b64_tr_b16 v[36:37], v124 offset:3072
	v_lshrrev_b32_e32 v43, 16, v43
	v_lshrrev_b32_e32 v42, 16, v42
	v_and_or_b32 v41, v41, s29, v42
	v_and_or_b32 v40, v40, s29, v43
	v_and_or_b32 v39, v39, s29, v45
	v_and_or_b32 v38, v38, s29, v44
	ds_read_b64_tr_b16 v[44:45], v124 offset:3136
	ds_read_b64_tr_b16 v[42:43], v124 offset:2112
	s_waitcnt lgkmcnt(2)
	v_mfma_f32_32x32x16_bf16 v[18:33], v[34:37], v[38:41], v[18:33]
	v_add_f32_e32 v34, v91, v111
	ds_bpermute_b32 v35, v184, v34
	s_waitcnt lgkmcnt(0)
	s_waitcnt lgkmcnt(0)
	v_add_f32_e32 v34, v34, v35
	v_mfma_f32_32x32x16_bf16 v[2:17], v[42:45], v[38:41], v[2:17]
	v_fmac_f32_e32 v34, v130, v0
	v_mov_b32_e32 v130, v34
	s_branch .LBB0_626
